# plus GQA attention QK^T fragment reads issued one step ahead (extra register buffer)
# baseline (speedup 1.0000x reference)
; __device__ __forceinline__ void finishSM(f32x16& p0, f32x16& p1, float alpha, float& l_reg, bf16x8& pa0, bf16x8& pa1, bf16x8& pa2, bf16x8& pa3) {
; #pragma unroll
;   for (int r = 0; r < 16; ++r) p1[r] = __builtin_amdgcn_exp2f(p1[r]);
;   float ps = 0;
; #pragma unroll
;   for (int r = 0; r < 16; ++r) ps += p0[r];
; #pragma unroll
;   for (int r = 0; r < 16; ++r) ps += p1[r];
;   { auto rr = __builtin_amdgcn_permlane32_swap(__float_as_uint(ps), __float_as_uint(ps), false, false);
;     ps = __uint_as_float(rr[0]) + __uint_as_float(rr[1]); }
;   l_reg = l_reg * alpha + ps;
;     ...
;   PK4(p0, 0, pa0); PK4(p0, 8, pa1); PK4(p1, 0, pa2); PK4(p1, 8, pa3);
;     ...
; }
; template <int DK, bool QL>
; __device__ __forceinline__ void qkt(f32x16& p0, f32x16& p1, const bf16* Ks, const bf16x8* qr, const char* ql, int r32, int hi) {
;   p0 = f32x16{}; p1 = f32x16{};
; #pragma unroll
;   for (int d0 = 0; d0 < DK / 16; ++d0) { int cb = (d0 * 16 + hi * 8) * 2;
;     const bf16x8 qv = QL ? *reinterpret_cast<const bf16x8*>(ql + d0 * 1024) : qr[d0];
;     bf16x8 b0 = *reinterpret_cast<const bf16x8*>((const char*)Ks + kswz<DK>(r32, cb));
;     bf16x8 b1 = *reinterpret_cast<const bf16x8*>((const char*)Ks + kswz<DK>(32 + r32, cb));
;     p0 = __builtin_amdgcn_mfma_f32_32x32x16_bf16(b0, qv, p0, 0, 0, 0);
;     p1 = __builtin_amdgcn_mfma_f32_32x32x16_bf16(b1, qv, p1, 0, 0, 0); }
.LBB0_660:
	ds_read_b128 v[66:69], v153
	ds_read_b128 v[70:73], v159 offset:49152
	ds_read_b128 v[74:77], v159 offset:57344
	ds_read_b128 v[218:221], v153 offset:1024
	ds_read_b128 v[222:225], v207 offset:49152
	ds_read_b128 v[226:229], v207 offset:57344
	ds_read_b128 v[168:171], v153 offset:2048
	ds_read_b128 v[194:197], v161 offset:49152
	ds_read_b128 v[244:247], v161 offset:57344
	v_add_f32_e32 v130, 0, v145
	v_add_f32_e32 v130, v216, v130
	s_waitcnt lgkmcnt(7)
	v_mfma_f32_32x32x16_bf16 v[82:97], v[70:73], v[66:69], 0
	v_add_f32_e32 v130, v131, v130
	v_add_f32_e32 v130, v215, v130
	v_add_f32_e32 v130, v132, v130
	v_add_f32_e32 v130, v144, v130
	v_add_f32_e32 v130, v133, v130
	v_add_f32_e32 v130, v143, v130
	v_add_f32_e32 v130, v140, v130
	s_waitcnt lgkmcnt(6)
	v_mfma_f32_32x32x16_bf16 v[66:81], v[74:77], v[66:69], 0
	v_add_f32_e32 v130, v142, v130
	v_add_f32_e32 v130, v139, v130
	v_add_f32_e32 v130, v141, v130
	v_exp_f32_e32 v126, v126
	v_add_f32_e32 v130, v136, v130
	v_exp_f32_e32 v127, v127
	v_add_f32_e32 v130, v138, v130
	s_waitcnt lgkmcnt(4)
	v_mfma_f32_32x32x16_bf16 v[82:97], v[222:225], v[218:221], v[82:97]
	v_exp_f32_e32 v124, v124
	v_add_f32_e32 v130, v135, v130
	v_exp_f32_e32 v125, v125
	v_add_f32_e32 v130, v137, v130
	v_exp_f32_e32 v118, v118
	v_add_f32_e32 v130, v126, v130
	v_exp_f32_e32 v119, v119
	s_waitcnt lgkmcnt(3)
	v_mfma_f32_32x32x16_bf16 v[66:81], v[226:229], v[218:221], v[66:81]
	ds_read_b128 v[218:221], v153 offset:3072
	ds_read_b128 v[222:225], v160 offset:49152
	ds_read_b128 v[226:229], v160 offset:57344
	v_add_f32_e32 v130, v127, v130
	v_exp_f32_e32 v116, v116
	v_add_f32_e32 v130, v124, v130
	v_exp_f32_e32 v117, v117
	v_add_f32_e32 v130, v125, v130
	v_exp_f32_e32 v114, v114
	s_waitcnt lgkmcnt(4)
	v_mfma_f32_32x32x16_bf16 v[82:97], v[194:197], v[168:171], v[82:97]
	v_add_f32_e32 v130, v118, v130
	v_exp_f32_e32 v115, v115
	v_add_f32_e32 v130, v119, v130
	v_exp_f32_e32 v128, v128
	v_add_f32_e32 v130, v116, v130
	v_exp_f32_e32 v129, v129
	v_add_f32_e32 v130, v117, v130
	s_waitcnt lgkmcnt(3)
	v_mfma_f32_32x32x16_bf16 v[66:81], v[244:247], v[168:171], v[66:81]
	ds_read_b128 v[168:171], v153 offset:4096
	ds_read_b128 v[194:197], v158 offset:49152
	ds_read_b128 v[244:247], v158 offset:57344
	v_exp_f32_e32 v122, v122
	v_add_f32_e32 v130, v114, v130
	v_exp_f32_e32 v123, v123
	v_add_f32_e32 v130, v115, v130
	v_exp_f32_e32 v120, v120
	v_add_f32_e32 v130, v128, v130
	s_waitcnt lgkmcnt(4)
	v_mfma_f32_32x32x16_bf16 v[82:97], v[222:225], v[218:221], v[82:97]
	v_exp_f32_e32 v121, v121
	v_add_f32_e32 v130, v129, v130
	v_add_f32_e32 v130, v122, v130
	v_add_f32_e32 v130, v123, v130
	v_add_f32_e32 v130, v120, v130
	v_add_f32_e32 v212, v121, v130
	v_mov_b32_e32 v213, v212
	s_waitcnt lgkmcnt(3)
	v_mfma_f32_32x32x16_bf16 v[66:81], v[226:229], v[218:221], v[66:81]
	ds_read_b128 v[218:221], v153 offset:5120
	ds_read_b128 v[222:225], v156 offset:49152
	ds_read_b128 v[226:229], v156 offset:57344
	v_permlane32_swap_b32_e32 v212, v213
	s_waitcnt lgkmcnt(4)
	v_mfma_f32_32x32x16_bf16 v[82:97], v[194:197], v[168:171], v[82:97]
	s_waitcnt lgkmcnt(3)
	v_mfma_f32_32x32x16_bf16 v[66:81], v[244:247], v[168:171], v[66:81]
	ds_read_b128 v[168:171], v153 offset:6144
	ds_read_b128 v[194:197], v157 offset:49152
	ds_read_b128 v[244:247], v157 offset:57344
	s_waitcnt lgkmcnt(4)
	v_mfma_f32_32x32x16_bf16 v[82:97], v[222:225], v[218:221], v[82:97]
	s_waitcnt lgkmcnt(3)
	v_mfma_f32_32x32x16_bf16 v[66:81], v[226:229], v[218:221], v[66:81]
	ds_read_b128 v[218:221], v153 offset:7168
	ds_read_b128 v[222:225], v176 offset:49152
	ds_read_b128 v[226:229], v176 offset:57344
	s_waitcnt lgkmcnt(4)
	v_mfma_f32_32x32x16_bf16 v[82:97], v[194:197], v[168:171], v[82:97]
	s_waitcnt lgkmcnt(3)
	v_mfma_f32_32x32x16_bf16 v[66:81], v[244:247], v[168:171], v[66:81]
	v_cvt_pk_bf16_f32 v130, v145, v216
	v_cvt_pk_bf16_f32 v131, v131, v215
	v_cvt_pk_bf16_f32 v132, v132, v144
	v_cvt_pk_bf16_f32 v133, v133, v143
	v_cvt_pk_bf16_f32 v140, v140, v142
	v_cvt_pk_bf16_f32 v141, v139, v141
	s_waitcnt lgkmcnt(1)
	v_mfma_f32_32x32x16_bf16 v[82:97], v[222:225], v[218:221], v[82:97]
	v_cvt_pk_bf16_f32 v142, v136, v138
	v_cvt_pk_bf16_f32 v143, v135, v137
	v_cvt_pk_bf16_f32 v136, v126, v127
	v_cvt_pk_bf16_f32 v137, v124, v125
	v_cvt_pk_bf16_f32 v138, v118, v119
	v_cvt_pk_bf16_f32 v139, v116, v117
	v_cvt_pk_bf16_f32 v214, v114, v115
	s_waitcnt lgkmcnt(0)
	v_mfma_f32_32x32x16_bf16 v[66:81], v[226:229], v[218:221], v[66:81]
	v_cvt_pk_bf16_f32 v215, v128, v129
	v_cvt_pk_bf16_f32 v216, v122, v123
	v_permlane32_swap_b32_e32 v130, v132
	v_cvt_pk_bf16_f32 v217, v120, v121
	v_permlane32_swap_b32_e32 v214, v216
	v_permlane32_swap_b32_e32 v131, v133
	v_permlane32_swap_b32_e32 v140, v142
	v_permlane32_swap_b32_e32 v141, v143
	v_permlane32_swap_b32_e32 v136, v138
	v_permlane32_swap_b32_e32 v137, v139
	v_permlane32_swap_b32_e32 v215, v217
	s_mov_b32 s2, 0xfff10000
	v_add_co_u32_e32 v118, vcc, s2, v146
	s_mov_b32 s2, 0xfff60000
	s_nop 0
	v_addc_co_u32_e32 v119, vcc, -1, v147, vcc
	v_add_co_u32_e32 v122, vcc, s2, v146
	s_nop 1
	v_addc_co_u32_e32 v123, vcc, -1, v147, vcc
	global_load_dwordx4 v[114:117], v[118:119], off
	s_nop 0
	global_load_dwordx4 v[118:121], v[118:119], off offset:-512
	s_nop 0
	global_load_dwordx4 v[126:129], v[122:123], off
	s_nop 0
	global_load_dwordx4 v[122:125], v[122:123], off offset:-512
	ds_read_b64_tr_b16 v[218:219], v152 offset:0
	ds_read_b64_tr_b16 v[220:221], v152 offset:0x800
	ds_read_b64_tr_b16 v[222:223], v152 offset:0x1000
	ds_read_b64_tr_b16 v[224:225], v152 offset:0x1800
	ds_read_b64_tr_b16 v[226:227], v152 offset:0x2000
	ds_read_b64_tr_b16 v[228:229], v152 offset:0x2800
	ds_read_b64_tr_b16 v[230:231], v152 offset:0x3000
	ds_read_b64_tr_b16 v[232:233], v152 offset:0x3800
	s_waitcnt lgkmcnt(0)
; #define SBAR() __builtin_amdgcn_sched_barrier(0)
; __device__ __forceinline__ void partialSM(f32x16& p0, f32x16& p1, float& m_reg, float& mn, float& alpha, float C, float thrRaw) {
;   float pmax = p0[0];
; #pragma unroll
;   for (int r = 1; r < 16; ++r) pmax = fmaxf(pmax, p0[r]);
; #pragma unroll
;   for (int r = 0; r < 16; ++r) pmax = fmaxf(pmax, p1[r]);
;   { auto rr = __builtin_amdgcn_permlane32_swap(__float_as_uint(pmax), __float_as_uint(pmax), false, false);
;     pmax = fmaxf(__uint_as_float(rr[0]), __uint_as_float(rr[1])); }
;   if (__builtin_expect(__all(pmax - m_reg <= thrRaw), 1)) { mn = m_reg; alpha = 1.f; }
;   else { mn = fmaxf(m_reg, pmax); alpha = __builtin_amdgcn_exp2f((m_reg - mn) * C); m_reg = mn; }
; template <int D0> __device__ __forceinline__ void pv_one(f32x16& od, int vb, bf16x8 pa0, bf16x8 pa1, bf16x8 pa2, bf16x8 pa3) {
;   const s16x4 l0 = tr_read<v_rd_off(D0, 0, 0)>(vb), h0 = tr_read<v_rd_off(D0, 0, 1)>(vb), l1 = tr_read<v_rd_off(D0, 1, 0)>(vb), h1 = tr_read<v_rd_off(D0, 1, 1)>(vb);
;   const s16x4 l2 = tr_read<v_rd_off(D0, 2, 0)>(vb), h2 = tr_read<v_rd_off(D0, 2, 1)>(vb), l3 = tr_read<v_rd_off(D0, 3, 0)>(vb), h3 = tr_read<v_rd_off(D0, 3, 1)>(vb);
;   asm volatile("s_waitcnt lgkmcnt(0)" ::: "memory"); SBAR();
;     ...
;   od = __builtin_amdgcn_mfma_f32_32x32x16_bf16(pa0, PK(l0, h0), od, 0, 0, 0);
;   od = __builtin_amdgcn_mfma_f32_32x32x16_bf16(pa1, PK(l1, h1), od, 0, 0, 0);
;   od = __builtin_amdgcn_mfma_f32_32x32x16_bf16(pa2, PK(l2, h2), od, 0, 0, 0);
;   od = __builtin_amdgcn_mfma_f32_32x32x16_bf16(pa3, PK(l3, h3), od, 0, 0, 0);
;     ...
; }
; __device__ __forceinline__ void pv_d0(f32x16* o, int vb, bf16x8 pa0, bf16x8 pa1, bf16x8 pa2, bf16x8 pa3) {
;   pv_one<0>(o[0], vb, pa0, pa1, pa2, pa3); pv_one<1>(o[1], vb, pa0, pa1, pa2, pa3); pv_one<2>(o[2], vb, pa0, pa1, pa2, pa3); pv_one<3>(o[3], vb, pa0, pa1, pa2, pa3);
	s_nop 0
	v_mfma_f32_32x32x16_bf16 v[18:33], v[130:133], v[218:221], v[18:33]
	ds_read_b64_tr_b16 v[218:219], v152 offset:0x200
	ds_read_b64_tr_b16 v[220:221], v152 offset:0xa00
	v_mfma_f32_32x32x16_bf16 v[18:33], v[140:143], v[222:225], v[18:33]
	ds_read_b64_tr_b16 v[222:223], v152 offset:0x1200
	ds_read_b64_tr_b16 v[224:225], v152 offset:0x1a00
	v_mfma_f32_32x32x16_bf16 v[18:33], v[136:139], v[226:229], v[18:33]
	ds_read_b64_tr_b16 v[226:227], v152 offset:0x2200
	ds_read_b64_tr_b16 v[228:229], v152 offset:0x2a00
	v_mfma_f32_32x32x16_bf16 v[18:33], v[214:217], v[230:233], v[18:33]
	ds_read_b64_tr_b16 v[230:231], v152 offset:0x3200
	ds_read_b64_tr_b16 v[232:233], v152 offset:0x3a00
	s_waitcnt lgkmcnt(0)
	v_mfma_f32_32x32x16_bf16 v[50:65], v[130:133], v[218:221], v[50:65]
	ds_read_b64_tr_b16 v[218:219], v152 offset:0x400
	ds_read_b64_tr_b16 v[220:221], v152 offset:0xc00
	v_mfma_f32_32x32x16_bf16 v[50:65], v[140:143], v[222:225], v[50:65]
	ds_read_b64_tr_b16 v[222:223], v152 offset:0x1400
	ds_read_b64_tr_b16 v[224:225], v152 offset:0x1c00
	v_mfma_f32_32x32x16_bf16 v[50:65], v[136:139], v[226:229], v[50:65]
	ds_read_b64_tr_b16 v[226:227], v152 offset:0x2400
	ds_read_b64_tr_b16 v[228:229], v152 offset:0x2c00
	v_mfma_f32_32x32x16_bf16 v[50:65], v[214:217], v[230:233], v[50:65]
	ds_read_b64_tr_b16 v[230:231], v152 offset:0x3400
	ds_read_b64_tr_b16 v[232:233], v152 offset:0x3c00
	s_waitcnt lgkmcnt(0)
	v_mfma_f32_32x32x16_bf16 v[2:17], v[130:133], v[218:221], v[2:17]
	ds_read_b64_tr_b16 v[218:219], v152 offset:0x600
	ds_read_b64_tr_b16 v[220:221], v152 offset:0xe00
	v_mfma_f32_32x32x16_bf16 v[2:17], v[140:143], v[222:225], v[2:17]
	ds_read_b64_tr_b16 v[222:223], v152 offset:0x1600
	ds_read_b64_tr_b16 v[224:225], v152 offset:0x1e00
	v_mfma_f32_32x32x16_bf16 v[2:17], v[136:139], v[226:229], v[2:17]
	ds_read_b64_tr_b16 v[226:227], v152 offset:0x2600
	ds_read_b64_tr_b16 v[228:229], v152 offset:0x2e00
	v_mfma_f32_32x32x16_bf16 v[2:17], v[214:217], v[230:233], v[2:17]
	ds_read_b64_tr_b16 v[230:231], v152 offset:0x3600
	ds_read_b64_tr_b16 v[232:233], v152 offset:0x3e00
	s_waitcnt lgkmcnt(0)
	v_mfma_f32_32x32x16_bf16 v[34:49], v[130:133], v[218:221], v[34:49]
	v_max_f32_e32 v130, v83, v83
	v_max_f32_e32 v131, v82, v82
	v_max_f32_e32 v130, v131, v130
	v_max3_f32 v130, v130, v84, v85
	v_max3_f32 v130, v130, v86, v87
	v_max3_f32 v130, v130, v88, v89
	v_max3_f32 v130, v130, v90, v91
	v_max3_f32 v130, v130, v92, v93
	v_max3_f32 v130, v130, v94, v95
	v_mfma_f32_32x32x16_bf16 v[34:49], v[140:143], v[222:225], v[34:49]
	v_max3_f32 v130, v130, v96, v97
	v_max3_f32 v130, v130, v66, v67
	v_max3_f32 v130, v130, v68, v69
	v_max3_f32 v130, v130, v70, v71
	v_max3_f32 v130, v130, v72, v73
	v_max3_f32 v130, v130, v74, v75
	v_max3_f32 v130, v130, v76, v77
	v_max3_f32 v130, v130, v78, v79
	v_mfma_f32_32x32x16_bf16 v[34:49], v[136:139], v[226:229], v[34:49]
	v_max3_f32 v130, v130, v80, v81
	v_mov_b32_e32 v131, v130
	s_nop 1
	v_permlane32_swap_b32_e32 v130, v131
	v_max_f32_e32 v131, v131, v131
	v_max_f32_e32 v130, v130, v130
	v_max_f32_e32 v130, v130, v131
	v_sub_f32_e32 v131, v130, v134
	s_mov_b32 s2, 0x42b504f3
	v_cmp_ge_f32_e32 vcc, s2, v131
	v_max_f32_e32 v131, v134, v134
	v_max_f32_e32 v130, v131, v130
	v_mfma_f32_32x32x16_bf16 v[34:49], v[214:217], v[230:233], v[34:49]
	v_sub_f32_e32 v131, v134, v130
	v_mul_f32_e32 v131, 0x3e0293ee, v131
	v_exp_f32_e32 v131, v131
	s_cmp_eq_u64 vcc, exec
	s_cselect_b64 s[2:3], -1, 0
	s_barrier
	s_waitcnt vmcnt(4)
	v_cndmask_b32_e64 v214, v131, 1.0, s[2:3]
	v_cmp_gt_f32_e32 vcc, 1.0, v214
	s_waitcnt vmcnt(4)
	ds_write_b128 v209, v[106:109]
	ds_write_b128 v210, v[110:113]
	ds_write_b128 v177, v[98:101] offset:32768
	ds_write_b128 v208, v[102:105] offset:32768
	s_cbranch_vccz .LBB0_664
	s_and_saveexec_b64 s[4:5], s[0:1]
	ds_write_b32 v149, v214 offset:128
	s_or_b64 exec, exec, s[4:5]
	s_waitcnt lgkmcnt(0)
	v_add_u32_e32 v131, v148, v0
	ds_read_b128 v[136:139], v131 offset:128
	ds_read_b128 v[140:143], v131 offset:160
	ds_read_b128 v[216:219], v131 offset:192
	ds_read_b128 v[220:223], v131 offset:224
	s_waitcnt lgkmcnt(3)
	v_pk_mul_f32 v[50:51], v[136:137], v[50:51]
	v_pk_mul_f32 v[52:53], v[52:53], v[138:139]
	s_waitcnt lgkmcnt(2)
	v_pk_mul_f32 v[54:55], v[54:55], v[140:141]
	v_pk_mul_f32 v[56:57], v[56:57], v[142:143]
	s_waitcnt lgkmcnt(1)
	v_pk_mul_f32 v[58:59], v[58:59], v[216:217]
	v_pk_mul_f32 v[60:61], v[60:61], v[218:219]
	s_waitcnt lgkmcnt(0)
	v_pk_mul_f32 v[62:63], v[62:63], v[220:221]
	v_pk_mul_f32 v[30:31], v[30:31], v[220:221]
	v_pk_mul_f32 v[26:27], v[26:27], v[216:217]
	v_pk_mul_f32 v[22:23], v[22:23], v[140:141]
	v_pk_mul_f32 v[32:33], v[32:33], v[222:223]
	v_pk_mul_f32 v[28:29], v[28:29], v[218:219]
	v_pk_mul_f32 v[24:25], v[24:25], v[142:143]
	v_pk_mul_f32 v[20:21], v[20:21], v[138:139]
	v_pk_mul_f32 v[18:19], v[18:19], v[136:137]
	v_pk_mul_f32 v[64:65], v[64:65], v[222:223]
	v_pk_mul_f32 v[34:35], v[136:137], v[34:35]
	v_pk_mul_f32 v[36:37], v[36:37], v[138:139]
	v_pk_mul_f32 v[38:39], v[38:39], v[140:141]
	v_pk_mul_f32 v[40:41], v[40:41], v[142:143]
	v_pk_mul_f32 v[42:43], v[42:43], v[216:217]
	v_pk_mul_f32 v[44:45], v[44:45], v[218:219]
	v_pk_mul_f32 v[46:47], v[46:47], v[220:221]
	v_pk_mul_f32 v[14:15], v[14:15], v[220:221]
	v_pk_mul_f32 v[10:11], v[10:11], v[216:217]
	v_pk_mul_f32 v[6:7], v[6:7], v[140:141]
	v_pk_mul_f32 v[16:17], v[16:17], v[222:223]
	v_pk_mul_f32 v[12:13], v[12:13], v[218:219]
	v_pk_mul_f32 v[8:9], v[8:9], v[142:143]
	v_pk_mul_f32 v[4:5], v[4:5], v[138:139]
	v_pk_mul_f32 v[2:3], v[2:3], v[136:137]
	v_pk_mul_f32 v[48:49], v[48:49], v[222:223]
; __device__ __forceinline__ void partialSM(f32x16& p0, f32x16& p1, float& m_reg, float& mn, float& alpha, float C, float thrRaw) {
;     ...
;   float mnC = -mn * C;
; #pragma unroll
;   for (int r = 0; r < 16; ++r) p0[r] = fmaf(p0[r], C, mnC);
; #pragma unroll
;   for (int r = 0; r < 16; ++r) p1[r] = fmaf(p1[r], C, mnC);
; #pragma unroll
;   for (int r = 0; r < 16; ++r) p0[r] = __builtin_amdgcn_exp2f(p0[r]);
.LBB0_664:
	v_cndmask_b32_e64 v215, v130, v134, s[2:3]
	v_mul_f32_e32 v216, 0xbe0293ee, v215
	v_fmamk_f32 v82, v82, 0x3e0293ee, v216
	v_fmamk_f32 v83, v83, 0x3e0293ee, v216
	v_fmamk_f32 v84, v84, 0x3e0293ee, v216
	v_fmamk_f32 v85, v85, 0x3e0293ee, v216
	v_fmamk_f32 v86, v86, 0x3e0293ee, v216
	v_fmamk_f32 v87, v87, 0x3e0293ee, v216
	v_fmamk_f32 v88, v88, 0x3e0293ee, v216
	v_fmamk_f32 v89, v89, 0x3e0293ee, v216
	v_fmamk_f32 v90, v90, 0x3e0293ee, v216
	v_fmamk_f32 v91, v91, 0x3e0293ee, v216
	v_fmamk_f32 v92, v92, 0x3e0293ee, v216
	v_fmamk_f32 v93, v93, 0x3e0293ee, v216
	v_fmamk_f32 v94, v94, 0x3e0293ee, v216
	v_fmamk_f32 v95, v95, 0x3e0293ee, v216
	v_fmamk_f32 v96, v96, 0x3e0293ee, v216
	v_fmamk_f32 v97, v97, 0x3e0293ee, v216
	v_exp_f32_e32 v130, v82
	v_exp_f32_e32 v145, v83
	v_exp_f32_e32 v131, v84
	v_exp_f32_e32 v144, v85
	v_exp_f32_e32 v132, v86
	v_exp_f32_e32 v143, v87
	v_exp_f32_e32 v133, v88
	v_exp_f32_e32 v142, v89
	v_exp_f32_e32 v134, v90
	v_exp_f32_e32 v141, v91
	v_exp_f32_e32 v135, v92
	v_exp_f32_e32 v140, v93
	v_exp_f32_e32 v136, v94
	v_exp_f32_e32 v139, v95
	v_exp_f32_e32 v137, v96
	v_exp_f32_e32 v138, v97
	v_fmamk_f32 v218, v71, 0x3e0293ee, v216
	v_fmamk_f32 v217, v78, 0x3e0293ee, v216
	s_add_i32 s8, s8, 2
	v_fmamk_f32 v225, v66, 0x3e0293ee, v216
	v_fmamk_f32 v226, v67, 0x3e0293ee, v216
	v_fmamk_f32 v227, v68, 0x3e0293ee, v216
	v_fmamk_f32 v228, v69, 0x3e0293ee, v216
	v_fmamk_f32 v229, v70, 0x3e0293ee, v216
	v_fmamk_f32 v219, v72, 0x3e0293ee, v216
	v_fmamk_f32 v220, v73, 0x3e0293ee, v216
	v_fmamk_f32 v221, v74, 0x3e0293ee, v216
	v_fmamk_f32 v222, v75, 0x3e0293ee, v216
	v_fmamk_f32 v223, v76, 0x3e0293ee, v216
	v_fmamk_f32 v224, v77, 0x3e0293ee, v216
	v_fmamk_f32 v230, v79, 0x3e0293ee, v216
	v_fmamk_f32 v231, v80, 0x3e0293ee, v216
	v_fmac_f32_e32 v216, 0x3e0293ee, v81
	s_waitcnt lgkmcnt(0)
	s_barrier
; __device__ __forceinline__ void finishSM(f32x16& p0, f32x16& p1, float alpha, float& l_reg, bf16x8& pa0, bf16x8& pa1, bf16x8& pa2, bf16x8& pa3) {
; #pragma unroll
;   for (int r = 0; r < 16; ++r) p1[r] = __builtin_amdgcn_exp2f(p1[r]);
;   float ps = 0;
; #pragma unroll
;   for (int r = 0; r < 16; ++r) ps += p0[r];
; #pragma unroll
;   for (int r = 0; r < 16; ++r) ps += p1[r];
;   { auto rr = __builtin_amdgcn_permlane32_swap(__float_as_uint(ps), __float_as_uint(ps), false, false);
;     ps = __uint_as_float(rr[0]) + __uint_as_float(rr[1]); }
;   l_reg = l_reg * alpha + ps;
;     ...
;   PK4(p0, 0, pa0); PK4(p0, 8, pa1); PK4(p1, 0, pa2); PK4(p1, 8, pa3);
; template <int DK, bool QL>
; __device__ __forceinline__ void qkt(f32x16& p0, f32x16& p1, const bf16* Ks, const bf16x8* qr, const char* ql, int r32, int hi) {
;   p0 = f32x16{}; p1 = f32x16{};
; #pragma unroll
;   for (int d0 = 0; d0 < DK / 16; ++d0) { int cb = (d0 * 16 + hi * 8) * 2;
;     const bf16x8 qv = QL ? *reinterpret_cast<const bf16x8*>(ql + d0 * 1024) : qr[d0];
;     bf16x8 b0 = *reinterpret_cast<const bf16x8*>((const char*)Ks + kswz<DK>(r32, cb));
;     bf16x8 b1 = *reinterpret_cast<const bf16x8*>((const char*)Ks + kswz<DK>(32 + r32, cb));
;     p0 = __builtin_amdgcn_mfma_f32_32x32x16_bf16(b0, qv, p0, 0, 0, 0);
;     p1 = __builtin_amdgcn_mfma_f32_32x32x16_bf16(b1, qv, p1, 0, 0, 0); }
	ds_read_b128 v[66:69], v153
	ds_read_b128 v[70:73], v159 offset:32768
	ds_read_b128 v[74:77], v159 offset:40960
	ds_read_b128 v[232:235], v153 offset:1024
	ds_read_b128 v[236:239], v207 offset:32768
	ds_read_b128 v[240:243], v207 offset:40960
	ds_read_b128 v[168:171], v153 offset:2048
	ds_read_b128 v[194:197], v161 offset:32768
	ds_read_b128 v[244:247], v161 offset:40960
	v_exp_f32_e32 v174, v219
	v_exp_f32_e32 v219, v221
	s_waitcnt lgkmcnt(7)
	v_mfma_f32_32x32x16_bf16 v[82:97], v[70:73], v[66:69], 0
	v_exp_f32_e32 v221, v223
	v_exp_f32_e32 v223, v217
	v_add_f32_e32 v217, 0, v130
	v_add_f32_e32 v217, v145, v217
	v_add_f32_e32 v217, v131, v217
	v_add_f32_e32 v217, v144, v217
	v_add_f32_e32 v217, v132, v217
	s_waitcnt lgkmcnt(6)
	v_mfma_f32_32x32x16_bf16 v[66:81], v[74:77], v[66:69], 0
	v_add_f32_e32 v217, v143, v217
	v_add_f32_e32 v217, v133, v217
	v_add_f32_e32 v217, v142, v217
	v_add_f32_e32 v217, v134, v217
	v_add_f32_e32 v217, v141, v217
	v_add_f32_e32 v217, v135, v217
	v_add_f32_e32 v217, v140, v217
	s_waitcnt lgkmcnt(4)
	v_mfma_f32_32x32x16_bf16 v[82:97], v[236:239], v[232:235], v[82:97]
	v_exp_f32_e32 v164, v225
	v_add_f32_e32 v217, v136, v217
	v_exp_f32_e32 v165, v226
	v_add_f32_e32 v217, v139, v217
	v_exp_f32_e32 v166, v227
	v_add_f32_e32 v217, v137, v217
	v_exp_f32_e32 v167, v228
	s_waitcnt lgkmcnt(3)
	v_mfma_f32_32x32x16_bf16 v[66:81], v[240:243], v[232:235], v[66:81]
	ds_read_b128 v[232:235], v153 offset:3072
	ds_read_b128 v[236:239], v160 offset:32768
	ds_read_b128 v[240:243], v160 offset:40960
	v_add_f32_e32 v217, v138, v217
	v_exp_f32_e32 v172, v229
	v_add_f32_e32 v217, v164, v217
	v_exp_f32_e32 v173, v218
	v_add_f32_e32 v217, v165, v217
	v_add_f32_e32 v217, v166, v217
	s_waitcnt lgkmcnt(4)
	v_mfma_f32_32x32x16_bf16 v[82:97], v[194:197], v[168:171], v[82:97]
	v_exp_f32_e32 v175, v220
	v_add_f32_e32 v217, v167, v217
	v_add_f32_e32 v217, v172, v217
	v_exp_f32_e32 v220, v222
	v_add_f32_e32 v217, v173, v217
	v_add_f32_e32 v217, v174, v217
	v_exp_f32_e32 v222, v224
	s_waitcnt lgkmcnt(3)
	v_mfma_f32_32x32x16_bf16 v[66:81], v[244:247], v[168:171], v[66:81]
	ds_read_b128 v[168:171], v153 offset:4096
	ds_read_b128 v[194:197], v158 offset:32768
	ds_read_b128 v[244:247], v158 offset:40960
	v_add_f32_e32 v217, v175, v217
	v_add_f32_e32 v217, v219, v217
	v_exp_f32_e32 v224, v230
	v_add_f32_e32 v217, v220, v217
	v_exp_f32_e32 v225, v231
	v_add_f32_e32 v217, v221, v217
	s_waitcnt lgkmcnt(4)
	v_mfma_f32_32x32x16_bf16 v[82:97], v[236:239], v[232:235], v[82:97]
	v_exp_f32_e32 v216, v216
	v_add_f32_e32 v217, v222, v217
	v_add_f32_e32 v217, v223, v217
	v_add_f32_e32 v217, v224, v217
	v_add_f32_e32 v217, v225, v217
	v_add_f32_e32 v217, v216, v217
	v_mov_b32_e32 v218, v217
	s_waitcnt lgkmcnt(3)
	v_mfma_f32_32x32x16_bf16 v[66:81], v[240:243], v[232:235], v[66:81]
	ds_read_b128 v[232:235], v153 offset:5120
	ds_read_b128 v[236:239], v156 offset:32768
	ds_read_b128 v[240:243], v156 offset:40960
	v_permlane32_swap_b32_e32 v217, v218
	s_waitcnt lgkmcnt(4)
	v_mfma_f32_32x32x16_bf16 v[82:97], v[194:197], v[168:171], v[82:97]
	s_waitcnt lgkmcnt(3)
	v_mfma_f32_32x32x16_bf16 v[66:81], v[244:247], v[168:171], v[66:81]
	ds_read_b128 v[168:171], v153 offset:6144
	ds_read_b128 v[194:197], v157 offset:32768
	ds_read_b128 v[244:247], v157 offset:40960
	s_waitcnt lgkmcnt(4)
	v_mfma_f32_32x32x16_bf16 v[82:97], v[236:239], v[232:235], v[82:97]
	s_waitcnt lgkmcnt(3)
	v_mfma_f32_32x32x16_bf16 v[66:81], v[240:243], v[232:235], v[66:81]
	ds_read_b128 v[232:235], v153 offset:7168
	ds_read_b128 v[236:239], v176 offset:32768
	ds_read_b128 v[240:243], v176 offset:40960
	s_waitcnt lgkmcnt(4)
	v_mfma_f32_32x32x16_bf16 v[82:97], v[194:197], v[168:171], v[82:97]
	s_waitcnt lgkmcnt(3)
	v_mfma_f32_32x32x16_bf16 v[66:81], v[244:247], v[168:171], v[66:81]
	v_cvt_pk_bf16_f32 v130, v130, v145
	v_cvt_pk_bf16_f32 v131, v131, v144
	v_cvt_pk_bf16_f32 v132, v132, v143
	v_cvt_pk_bf16_f32 v133, v133, v142
	v_cvt_pk_bf16_f32 v134, v134, v141
	v_cvt_pk_bf16_f32 v135, v135, v140
	s_waitcnt lgkmcnt(1)
	v_mfma_f32_32x32x16_bf16 v[82:97], v[236:239], v[232:235], v[82:97]
	v_cvt_pk_bf16_f32 v136, v136, v139
	v_cvt_pk_bf16_f32 v137, v137, v138
	v_cvt_pk_bf16_f32 v138, v164, v165
	v_cvt_pk_bf16_f32 v139, v166, v167
	v_cvt_pk_bf16_f32 v140, v172, v173
	v_cvt_pk_bf16_f32 v141, v174, v175
	v_cvt_pk_bf16_f32 v142, v219, v220
	s_waitcnt lgkmcnt(0)
	v_mfma_f32_32x32x16_bf16 v[66:81], v[240:243], v[232:235], v[66:81]
	v_cvt_pk_bf16_f32 v143, v221, v222
	v_cvt_pk_bf16_f32 v144, v223, v224
	v_cvt_pk_bf16_f32 v145, v225, v216
	v_permlane32_swap_b32_e32 v130, v132
	v_permlane32_swap_b32_e32 v131, v133
	v_permlane32_swap_b32_e32 v134, v136
	v_permlane32_swap_b32_e32 v135, v137
	v_permlane32_swap_b32_e32 v138, v140
	v_permlane32_swap_b32_e32 v139, v141
	v_permlane32_swap_b32_e32 v142, v144
	v_permlane32_swap_b32_e32 v143, v145
	s_cmp_gt_u32 s8, 60
	s_cselect_b64 s[4:5], -1, 0
	s_and_b64 vcc, exec, s[4:5]
	s_cbranch_vccnz .LBB0_666
	v_add_co_u32_e32 v98, vcc, 0xfffb0000, v146
	s_nop 1
	v_addc_co_u32_e32 v99, vcc, -1, v147, vcc
	global_load_dwordx4 v[106:109], v[98:99], off
	s_nop 0
	global_load_dwordx4 v[98:101], v[98:99], off offset:-512
	s_nop 0
	global_load_dwordx4 v[110:113], v[146:147], off
	global_load_dwordx4 v[102:105], v[146:147], off offset:-512

; #define SBAR() __builtin_amdgcn_sched_barrier(0)
; __device__ __forceinline__ void partialSM(f32x16& p0, f32x16& p1, float& m_reg, float& mn, float& alpha, float C, float thrRaw) {
;     ...
;   float mnC = -mn * C;
; #pragma unroll
;   for (int r = 0; r < 16; ++r) p0[r] = fmaf(p0[r], C, mnC);
; #pragma unroll
;   for (int r = 0; r < 16; ++r) p1[r] = fmaf(p1[r], C, mnC);
; #pragma unroll
;   for (int r = 0; r < 16; ++r) p0[r] = __builtin_amdgcn_exp2f(p0[r]);
; }
; __device__ __forceinline__ void finishSM(f32x16& p0, f32x16& p1, float alpha, float& l_reg, bf16x8& pa0, bf16x8& pa1, bf16x8& pa2, bf16x8& pa3) {
; #pragma unroll
;   for (int r = 0; r < 16; ++r) p1[r] = __builtin_amdgcn_exp2f(p1[r]);
;   float ps = 0;
; #pragma unroll
;   for (int r = 0; r < 16; ++r) ps += p0[r];
; #pragma unroll
;   for (int r = 0; r < 16; ++r) ps += p1[r];
;   { auto rr = __builtin_amdgcn_permlane32_swap(__float_as_uint(ps), __float_as_uint(ps), false, false);
;     ps = __uint_as_float(rr[0]) + __uint_as_float(rr[1]); }
;   l_reg = l_reg * alpha + ps;
;     ...
;   PK4(p0, 0, pa0); PK4(p0, 8, pa1); PK4(p1, 0, pa2); PK4(p1, 8, pa3);
;     ...
; }
; template <int D0> __device__ __forceinline__ void pv_one(f32x16& od, int vb, bf16x8 pa0, bf16x8 pa1, bf16x8 pa2, bf16x8 pa3) {
;   const s16x4 l0 = tr_read<v_rd_off(D0, 0, 0)>(vb), h0 = tr_read<v_rd_off(D0, 0, 1)>(vb), l1 = tr_read<v_rd_off(D0, 1, 0)>(vb), h1 = tr_read<v_rd_off(D0, 1, 1)>(vb);
;   const s16x4 l2 = tr_read<v_rd_off(D0, 2, 0)>(vb), h2 = tr_read<v_rd_off(D0, 2, 1)>(vb), l3 = tr_read<v_rd_off(D0, 3, 0)>(vb), h3 = tr_read<v_rd_off(D0, 3, 1)>(vb);
;   asm volatile("s_waitcnt lgkmcnt(0)" ::: "memory"); SBAR();
;     ...
;   od = __builtin_amdgcn_mfma_f32_32x32x16_bf16(pa0, PK(l0, h0), od, 0, 0, 0);
;   od = __builtin_amdgcn_mfma_f32_32x32x16_bf16(pa1, PK(l1, h1), od, 0, 0, 0);
;   od = __builtin_amdgcn_mfma_f32_32x32x16_bf16(pa2, PK(l2, h2), od, 0, 0, 0);
;   od = __builtin_amdgcn_mfma_f32_32x32x16_bf16(pa3, PK(l3, h3), od, 0, 0, 0);
.LBB0_676:
	v_cndmask_b32_e64 v99, v99, v134, s[2:3]
	v_mul_f32_e32 v99, 0xbe0293ee, v99
	v_fmamk_f32 v82, v82, 0x3e0293ee, v99
	v_fmamk_f32 v83, v83, 0x3e0293ee, v99
	v_fmamk_f32 v100, v84, 0x3e0293ee, v99
	v_exp_f32_e32 v84, v82
	v_fmamk_f32 v101, v86, 0x3e0293ee, v99
	v_exp_f32_e32 v86, v83
	v_fmamk_f32 v85, v85, 0x3e0293ee, v99
	v_exp_f32_e32 v82, v100
	v_fmamk_f32 v66, v66, 0x3e0293ee, v99
	v_exp_f32_e32 v85, v85
	v_fmamk_f32 v104, v87, 0x3e0293ee, v99
	v_fmamk_f32 v113, v96, 0x3e0293ee, v99
	v_fmamk_f32 v96, v77, 0x3e0293ee, v99
	v_exp_f32_e32 v77, v101
	v_exp_f32_e32 v100, v66
	v_add_f32_e32 v66, 0, v84
	v_fmamk_f32 v105, v88, 0x3e0293ee, v99
	v_exp_f32_e32 v83, v104
	v_add_f32_e32 v66, v86, v66
	v_fmamk_f32 v106, v89, 0x3e0293ee, v99
	v_fmamk_f32 v112, v95, 0x3e0293ee, v99
	v_fmamk_f32 v95, v76, 0x3e0293ee, v99
	v_exp_f32_e32 v76, v105
	v_add_f32_e32 v66, v82, v66
	v_fmamk_f32 v107, v90, 0x3e0293ee, v99
	v_fmamk_f32 v114, v97, 0x3e0293ee, v99
	v_fmamk_f32 v97, v78, 0x3e0293ee, v99
	v_exp_f32_e32 v78, v106
	v_add_f32_e32 v66, v85, v66
	v_fmamk_f32 v108, v91, 0x3e0293ee, v99
	v_fmamk_f32 v109, v92, 0x3e0293ee, v99
	v_fmamk_f32 v92, v73, 0x3e0293ee, v99
	v_exp_f32_e32 v73, v107
	v_add_f32_e32 v66, v77, v66
	v_fmamk_f32 v111, v94, 0x3e0293ee, v99
	v_fmamk_f32 v94, v75, 0x3e0293ee, v99
	v_exp_f32_e32 v75, v108
	v_add_f32_e32 v66, v83, v66
	v_fmamk_f32 v110, v93, 0x3e0293ee, v99
	v_fmamk_f32 v90, v71, 0x3e0293ee, v99
	v_exp_f32_e32 v71, v109
	v_add_f32_e32 v66, v76, v66
	v_fmamk_f32 v93, v74, 0x3e0293ee, v99
	v_exp_f32_e32 v74, v110
	v_add_f32_e32 v66, v78, v66
	v_fmamk_f32 v88, v69, 0x3e0293ee, v99
	v_exp_f32_e32 v69, v111
	v_add_f32_e32 v66, v73, v66
	v_fmamk_f32 v91, v72, 0x3e0293ee, v99
	v_exp_f32_e32 v72, v112
	v_add_f32_e32 v66, v75, v66
	v_fmamk_f32 v87, v68, 0x3e0293ee, v99
	v_exp_f32_e32 v68, v113
	v_add_f32_e32 v66, v71, v66
	v_fmamk_f32 v89, v70, 0x3e0293ee, v99
	v_exp_f32_e32 v70, v114
	v_add_f32_e32 v66, v74, v66
	v_fmamk_f32 v67, v67, 0x3e0293ee, v99
	v_add_f32_e32 v66, v69, v66
	v_exp_f32_e32 v101, v67
	v_add_f32_e32 v66, v72, v66
	v_exp_f32_e32 v87, v87
	v_add_f32_e32 v66, v68, v66
	v_exp_f32_e32 v88, v88
	v_add_f32_e32 v66, v70, v66
	v_exp_f32_e32 v89, v89
	v_add_f32_e32 v66, v100, v66
	v_exp_f32_e32 v90, v90
	v_add_f32_e32 v66, v101, v66
	v_exp_f32_e32 v91, v91
	v_add_f32_e32 v66, v87, v66
	v_exp_f32_e32 v92, v92
	v_add_f32_e32 v66, v88, v66
	v_exp_f32_e32 v93, v93
	v_add_f32_e32 v66, v89, v66
	v_exp_f32_e32 v94, v94
	v_add_f32_e32 v66, v90, v66
	v_exp_f32_e32 v95, v95
	v_add_f32_e32 v66, v91, v66
	v_exp_f32_e32 v96, v96
	v_add_f32_e32 v66, v92, v66
	v_fmamk_f32 v79, v79, 0x3e0293ee, v99
	v_exp_f32_e32 v97, v97
	v_add_f32_e32 v66, v93, v66
	v_fmamk_f32 v80, v80, 0x3e0293ee, v99
	v_exp_f32_e32 v104, v79
	v_add_f32_e32 v66, v94, v66
	v_fmac_f32_e32 v99, 0x3e0293ee, v81
	v_exp_f32_e32 v105, v80
	v_add_f32_e32 v66, v95, v66
	v_exp_f32_e32 v99, v99
	v_add_f32_e32 v66, v96, v66
	v_add_f32_e32 v66, v97, v66
	v_add_f32_e32 v66, v104, v66
	v_add_f32_e32 v66, v105, v66
	v_add_f32_e32 v66, v99, v66
	v_mov_b32_e32 v67, v66
	s_mov_b64 s[4:5], 0x800
	s_nop 0
	v_permlane32_swap_b32_e32 v66, v67
	v_cvt_pk_bf16_f32 v80, v84, v86
	v_cvt_pk_bf16_f32 v81, v82, v85
	v_cvt_pk_bf16_f32 v82, v77, v83
	v_cvt_pk_bf16_f32 v83, v76, v78
	v_cvt_pk_bf16_f32 v76, v73, v75
	v_cvt_pk_bf16_f32 v77, v71, v74
	v_cvt_pk_bf16_f32 v78, v69, v72
	v_cvt_pk_bf16_f32 v79, v68, v70
	v_cvt_pk_bf16_f32 v68, v100, v101
	v_cvt_pk_bf16_f32 v69, v87, v88
	v_cvt_pk_bf16_f32 v70, v89, v90
	v_cvt_pk_bf16_f32 v71, v91, v92
	v_cvt_pk_bf16_f32 v72, v93, v94
	v_cvt_pk_bf16_f32 v73, v95, v96
	v_cvt_pk_bf16_f32 v74, v97, v104
	v_cvt_pk_bf16_f32 v75, v105, v99
	s_nop 0
	v_permlane32_swap_b32_e32 v80, v82
	v_permlane32_swap_b32_e32 v81, v83
	v_permlane32_swap_b32_e32 v76, v78
	v_permlane32_swap_b32_e32 v77, v79
	v_permlane32_swap_b32_e32 v68, v70
	v_permlane32_swap_b32_e32 v69, v71
	v_permlane32_swap_b32_e32 v72, v74
	v_permlane32_swap_b32_e32 v73, v75
	ds_read_b64_tr_b16 v[84:85], v151 offset:0
	ds_read_b64_tr_b16 v[86:87], v151 offset:0x800
	ds_read_b64_tr_b16 v[88:89], v151 offset:0x1000
	ds_read_b64_tr_b16 v[90:91], v151 offset:0x1800
	ds_read_b64_tr_b16 v[92:93], v151 offset:0x2000
	ds_read_b64_tr_b16 v[94:95], v151 offset:0x2800
	ds_read_b64_tr_b16 v[104:105], v151 offset:0x3000
	ds_read_b64_tr_b16 v[106:107], v151 offset:0x3800
	s_waitcnt lgkmcnt(0)
	s_nop 0
	v_mfma_f32_32x32x16_bf16 v[18:33], v[80:83], v[84:87], v[18:33]
	ds_read_b64_tr_b16 v[84:85], v151 offset:0x200
	ds_read_b64_tr_b16 v[86:87], v151 offset:0xa00
	v_mfma_f32_32x32x16_bf16 v[18:33], v[76:79], v[88:91], v[18:33]
	ds_read_b64_tr_b16 v[88:89], v151 offset:0x1200
	ds_read_b64_tr_b16 v[90:91], v151 offset:0x1a00
	v_mfma_f32_32x32x16_bf16 v[18:33], v[68:71], v[92:95], v[18:33]
	ds_read_b64_tr_b16 v[92:93], v151 offset:0x2200
	ds_read_b64_tr_b16 v[94:95], v151 offset:0x2a00
	v_mfma_f32_32x32x16_bf16 v[18:33], v[72:75], v[104:107], v[18:33]
	ds_read_b64_tr_b16 v[104:105], v151 offset:0x3200
	ds_read_b64_tr_b16 v[106:107], v151 offset:0x3a00
	s_waitcnt lgkmcnt(0)
	v_mfma_f32_32x32x16_bf16 v[50:65], v[80:83], v[84:87], v[50:65]
	ds_read_b64_tr_b16 v[84:85], v151 offset:0x400
	ds_read_b64_tr_b16 v[86:87], v151 offset:0xc00
	v_mfma_f32_32x32x16_bf16 v[50:65], v[76:79], v[88:91], v[50:65]
	ds_read_b64_tr_b16 v[88:89], v151 offset:0x1400
	ds_read_b64_tr_b16 v[90:91], v151 offset:0x1c00
	v_mfma_f32_32x32x16_bf16 v[50:65], v[68:71], v[92:95], v[50:65]
	ds_read_b64_tr_b16 v[92:93], v151 offset:0x2400
	ds_read_b64_tr_b16 v[94:95], v151 offset:0x2c00
	v_mfma_f32_32x32x16_bf16 v[50:65], v[72:75], v[104:107], v[50:65]
	ds_read_b64_tr_b16 v[104:105], v151 offset:0x3400
	ds_read_b64_tr_b16 v[106:107], v151 offset:0x3c00
	s_waitcnt lgkmcnt(0)
; __device__ __forceinline__ int opaque_tid() { int t = threadIdx.x; asm volatile("" : "+v"(t)); return t; }
; __device__ __forceinline__ int crow(int r, int hi) { return (r & 3) + 8 * (r >> 2) + 4 * hi; }
; template <int DK, bool NA, bool QL, int SD> ...
;     ...
;   if (hi == 0) li_l[r32] = l_reg; asm volatile("s_waitcnt vmcnt(0) lgkmcnt(0)" ::: "memory");
; #pragma unroll
;   for (int r = 0; r < 16; ++r) { const float rl = __builtin_amdgcn_rcpf(li_l[crow(r, hi)]);
; #pragma unroll
;     for (int d = 0; d < 4; ++d) o[d][r] *= rl; }
; __device__ __forceinline__ void store_o_bf16(const att::f32x16 (&o)[4], bf16* base  , unsigned char* lds) {
;     const int tid = opaque_tid(), lane = tid & 63, wave = __builtin_amdgcn_readfirstlane(tid >> 6), r32 = lane & 31, hi = lane >> 5;
;     __syncthreads();
;     float* T = (float*)(lds + wave * 16896);
	v_mfma_f32_32x32x16_bf16 v[2:17], v[80:83], v[84:87], v[2:17]
	ds_read_b64_tr_b16 v[84:85], v151 offset:0x600
	ds_read_b64_tr_b16 v[86:87], v151 offset:0xe00
	v_mfma_f32_32x32x16_bf16 v[2:17], v[76:79], v[88:91], v[2:17]
	ds_read_b64_tr_b16 v[88:89], v151 offset:0x1600
	ds_read_b64_tr_b16 v[90:91], v151 offset:0x1e00
	v_mfma_f32_32x32x16_bf16 v[2:17], v[68:71], v[92:95], v[2:17]
	ds_read_b64_tr_b16 v[92:93], v151 offset:0x2600
	ds_read_b64_tr_b16 v[94:95], v151 offset:0x2e00
	v_mfma_f32_32x32x16_bf16 v[2:17], v[72:75], v[104:107], v[2:17]
	ds_read_b64_tr_b16 v[104:105], v151 offset:0x3600
	ds_read_b64_tr_b16 v[106:107], v151 offset:0x3e00
	s_waitcnt lgkmcnt(0)
	v_mfma_f32_32x32x16_bf16 v[34:49], v[80:83], v[84:87], v[34:49]
	v_mfma_f32_32x32x16_bf16 v[34:49], v[76:79], v[88:91], v[34:49]
	v_mfma_f32_32x32x16_bf16 v[34:49], v[68:71], v[92:95], v[34:49]
	v_mfma_f32_32x32x16_bf16 v[34:49], v[72:75], v[104:107], v[34:49]
	s_and_saveexec_b64 s[2:3], s[0:1]
	v_add_f32_e32 v68, v102, v103
	v_fmac_f32_e32 v68, v150, v130
	v_add_f32_e32 v66, v66, v67
	v_fmac_f32_e32 v66, v68, v98
	ds_write_b32 v149, v66
	s_or_b64 exec, exec, s[2:3]
	s_waitcnt vmcnt(0) lgkmcnt(0)
	v_add_u32_e32 v0, v148, v0
	ds_read_b128 v[66:69], v0
	ds_read_b128 v[70:73], v0 offset:32
	v_readlane_b32 s2, v253, 7
	v_readlane_b32 s3, v253, 8
	s_waitcnt lgkmcnt(1)
	v_rcp_f32_e32 v66, v66
	v_rcp_f32_e32 v67, v67
	v_mul_f32_e32 v75, v66, v2
	v_rcp_f32_e32 v2, v68
	v_mul_f32_e32 v68, v67, v3
	v_rcp_f32_e32 v3, v69
	v_mul_f32_e32 v74, v66, v18
	v_mul_f32_e32 v50, v66, v50
	v_mul_f32_e32 v34, v66, v34
	v_mul_f32_e32 v66, v67, v19
	v_mul_f32_e32 v51, v67, v51
	v_mul_f32_e32 v35, v67, v35
	v_mul_f32_e32 v67, v2, v20
	v_mul_f32_e32 v52, v2, v52
	v_mul_f32_e32 v69, v2, v4
	v_mul_f32_e32 v36, v2, v36
	v_mul_f32_e32 v76, v3, v21
	s_waitcnt lgkmcnt(0)
	v_rcp_f32_e32 v2, v70
	v_mul_f32_e32 v53, v3, v53
	v_mul_f32_e32 v70, v3, v5
	v_mul_f32_e32 v37, v3, v37
	v_rcp_f32_e32 v3, v71
	v_rcp_f32_e32 v18, v72
	v_mul_f32_e32 v22, v2, v22
	v_mul_f32_e32 v54, v2, v54
	v_mul_f32_e32 v6, v2, v6
	v_mul_f32_e32 v38, v2, v38
	v_mul_f32_e32 v23, v3, v23
	v_mul_f32_e32 v55, v3, v55
	v_mul_f32_e32 v7, v3, v7
	v_mul_f32_e32 v39, v3, v39
	v_mul_f32_e32 v24, v18, v24
	v_mul_f32_e32 v56, v18, v56
	ds_read_b128 v[2:5], v0 offset:64
	v_mul_f32_e32 v8, v18, v8
	v_mul_f32_e32 v40, v18, v40
	ds_read_b128 v[18:21], v0 offset:96
	v_rcp_f32_e32 v71, v73
	s_waitcnt lgkmcnt(1)
	v_rcp_f32_e32 v0, v2
	v_rcp_f32_e32 v3, v3
	v_rcp_f32_e32 v4, v4
	v_rcp_f32_e32 v5, v5
	s_waitcnt lgkmcnt(0)
	v_rcp_f32_e32 v18, v18
	v_rcp_f32_e32 v19, v19
	v_rcp_f32_e32 v20, v20
	v_rcp_f32_e32 v21, v21
	v_mul_f32_e32 v2, v71, v57
	v_mul_f32_e32 v26, v0, v26
	v_mul_f32_e32 v57, v0, v58
	v_mul_f32_e32 v10, v0, v10
	v_mul_f32_e32 v0, v0, v42
	v_mul_f32_e32 v27, v3, v27
	v_mul_f32_e32 v42, v3, v59
	v_mul_f32_e32 v11, v3, v11
	v_mul_f32_e32 v3, v3, v43
	v_mul_f32_e32 v28, v4, v28
	v_mul_f32_e32 v43, v4, v60
	v_mul_f32_e32 v12, v4, v12
	v_mul_f32_e32 v4, v4, v44
	v_mul_f32_e32 v29, v5, v29
	v_mul_f32_e32 v44, v5, v61
	v_mul_f32_e32 v13, v5, v13
	v_mul_f32_e32 v5, v5, v45
	v_mul_f32_e32 v30, v18, v30
	v_mul_f32_e32 v45, v18, v62
	v_mul_f32_e32 v14, v18, v14
	v_mul_f32_e32 v18, v18, v46
	v_mul_f32_e32 v31, v19, v31
	v_mul_f32_e32 v46, v19, v63
	v_mul_f32_e32 v15, v19, v15
	v_mul_f32_e32 v19, v19, v47
	v_mul_f32_e32 v32, v20, v32
	v_mul_f32_e32 v47, v20, v64
	v_mul_f32_e32 v16, v20, v16
	v_mul_f32_e32 v20, v20, v48
	v_mul_f32_e32 v33, v21, v33
	v_mul_f32_e32 v48, v21, v65
	v_mul_f32_e32 v17, v21, v17
	v_mul_f32_e32 v21, v21, v49
	v_mov_b32_e32 v49, v188
	s_nop 0
	v_readfirstlane_b32 s0, v49
	s_ashr_i32 s0, s0, 6
	v_lshrrev_b32_e32 v59, 3, v49
	v_and_b32_e32 v58, 31, v49
	s_mul_i32 s1, s0, 0x4200
	v_and_b32_e32 v59, 4, v59
	s_add_i32 s1, s1, 0
	v_lshlrev_b32_e32 v58, 2, v58
	v_mul_u32_u24_e32 v59, 0x210, v59
	v_add3_u32 v58, s1, v58, v59
	s_barrier
; __device__ __forceinline__ int opaque_tid() { int t = threadIdx.x; asm volatile("" : "+v"(t)); return t; }
; __device__ __forceinline__ int crow(int r, int hi) { return (r & 3) + 8 * (r >> 2) + 4 * hi; }
; __device__ __forceinline__ unsigned cvtpk(float lo, float hi) { unsigned r; asm volatile("v_cvt_pk_bf16_f32 %0, %1, %2" : "=v"(r) : "v"(lo), "v"(hi)); return r; }
; __device__ __forceinline__ void store_o_bf16(const att::f32x16 (&o)[4], bf16* base  , unsigned char* lds) {
;     const int tid = opaque_tid(), lane = tid & 63, wave = __builtin_amdgcn_readfirstlane(tid >> 6), r32 = lane & 31, hi = lane >> 5;
;     __syncthreads();
;     float* T = (float*)(lds + wave * 16896);
; #pragma unroll
;     for (int r = 0; r < 16; ++r) { float* tp = T + att::crow(r, hi) * 132 + r32;
; #pragma unroll
;         for (int d = 0; d < 4; ++d) tp[32 * d] = o[d][r]; }
; #pragma unroll
;     for (int k = 0; k < 8; ++k) { const int chunk = k * 64 + lane, row = chunk >> 4, c8 = chunk & 15;
;         const f32x4 a = *(const f32x4*)(T + row * 132 + c8 * 8), b = *(const f32x4*)(T + row * 132 + c8 * 8 + 4);
;         v4u w; w.x = att::cvtpk(a.x, a.y); w.y = att::cvtpk(a.z, a.w); w.z = att::cvtpk(b.x, b.y); w.w = att::cvtpk(b.z, b.w);
;         *(v4u*)(base + (size_t)(wave * 32 + row) * DM + c8 * 8) = w; }
; }
	ds_write2_b32 v58, v74, v50 offset1:32
	ds_write2_b32 v58, v75, v34 offset0:64 offset1:96
	ds_write2_b32 v58, v66, v51 offset0:132 offset1:164
	ds_write2_b32 v58, v68, v35 offset0:196 offset1:228
	v_add_u32_e32 v34, 0x400, v58
	ds_write2_b32 v34, v67, v52 offset0:8 offset1:40
	ds_write2_b32 v34, v69, v36 offset0:72 offset1:104
	ds_write2_b32 v34, v76, v53 offset0:140 offset1:172
	ds_write2_b32 v34, v70, v37 offset0:204 offset1:236
	v_add_u32_e32 v34, 0x1000, v58
	ds_write2_b32 v34, v22, v54 offset0:32 offset1:64
	ds_write2_b32 v34, v6, v38 offset0:96 offset1:128
	ds_write2_b32 v34, v23, v55 offset0:164 offset1:196
	v_add_u32_e32 v6, 0x1200, v58
	ds_write2_b32 v6, v7, v39 offset0:100 offset1:132
	v_add_u32_e32 v6, 0x1400, v58
	v_mul_f32_e32 v25, v71, v25
	v_mul_f32_e32 v9, v71, v9
	v_mul_f32_e32 v41, v71, v41
	ds_write2_b32 v6, v24, v56 offset0:40 offset1:72
	ds_write2_b32 v6, v8, v40 offset0:104 offset1:136
	ds_write2_b32 v6, v25, v2 offset0:172 offset1:204
	v_add_u32_e32 v2, 0x1600, v58
	ds_write2_b32 v2, v9, v41 offset0:108 offset1:140
	v_add_u32_e32 v2, 0x2000, v58
	ds_write2_b32 v2, v26, v57 offset0:64 offset1:96
	ds_write2_b32 v2, v10, v0 offset0:128 offset1:160
	ds_write2_b32 v2, v27, v42 offset0:196 offset1:228
	v_add_u32_e32 v0, 0x2400, v58
	ds_write2_b32 v0, v11, v3 offset0:4 offset1:36
	ds_write2_b32 v0, v28, v43 offset0:72 offset1:104
	ds_write2_b32 v0, v12, v4 offset0:136 offset1:168
	ds_write2_b32 v0, v29, v44 offset0:204 offset1:236
	v_add_u32_e32 v0, 0x2800, v58
	ds_write2_b32 v0, v13, v5 offset0:12 offset1:44
	v_add_u32_e32 v0, 0x3000, v58
	ds_write2_b32 v0, v30, v45 offset0:96 offset1:128
	ds_write2_b32 v0, v14, v18 offset0:160 offset1:192
	v_add_u32_e32 v0, 0x3200, v58
	ds_write2_b32 v0, v31, v46 offset0:100 offset1:132
	v_add_u32_e32 v0, 0x3400, v58
	ds_write2_b32 v0, v15, v19 offset0:36 offset1:68
	ds_write2_b32 v0, v32, v47 offset0:104 offset1:136
	ds_write2_b32 v0, v16, v20 offset0:168 offset1:200
	v_add_u32_e32 v0, 0x3600, v58
	ds_write2_b32 v0, v33, v48 offset0:108 offset1:140
	v_add_u32_e32 v0, 0x3800, v58
	ds_write2_b32 v0, v17, v21 offset0:44 offset1:76
	v_lshlrev_b32_e32 v0, 3, v49
	v_and_b32_e32 v0, 0x78, v0
	v_bfe_u32 v12, v49, 4, 2
	v_lshlrev_b32_e32 v2, 2, v0
	v_mul_u32_u24_e32 v3, 0x210, v12
	v_lshl_or_b32 v18, s0, 5, v12
	v_add3_u32 v22, s1, v2, v3
	v_lshlrev_b32_e32 v0, 1, v0
	v_ashrrev_i32_e32 v19, 31, v18
	ds_read_b128 v[2:5], v22
	ds_read_b128 v[8:11], v22 offset:16
	v_lshl_add_u64 v[16:17], s[2:3], 0, v[0:1]
	v_lshlrev_b64 v[20:21], 12, v[18:19]
	s_waitcnt lgkmcnt(1)
	v_cvt_pk_bf16_f32 v2, v2, v3
	v_cvt_pk_bf16_f32 v3, v4, v5
	s_waitcnt lgkmcnt(0)
	v_cvt_pk_bf16_f32 v4, v8, v9
	v_cvt_pk_bf16_f32 v5, v10, v11
	ds_read_b128 v[8:11], v22 offset:2112
	ds_read_b128 v[12:15], v22 offset:2128
	v_lshl_add_u64 v[20:21], v[16:17], 0, v[20:21]
	global_store_dwordx4 v[20:21], v[2:5], off offset:2048
	v_lshl_add_u64 v[6:7], v[16:17], 0, s[4:5]
	s_waitcnt lgkmcnt(1)
	v_cvt_pk_bf16_f32 v2, v8, v9
	v_cvt_pk_bf16_f32 v3, v10, v11
	s_waitcnt lgkmcnt(0)
	v_cvt_pk_bf16_f32 v4, v12, v13
	v_or_b32_e32 v12, 4, v18
	v_ashrrev_i32_e32 v13, 31, v12
	v_lshlrev_b64 v[20:21], 12, v[12:13]
	v_cvt_pk_bf16_f32 v5, v14, v15
	ds_read_b128 v[8:11], v22 offset:4224
	ds_read_b128 v[12:15], v22 offset:4240
	v_lshl_add_u64 v[20:21], v[16:17], 0, v[20:21]
	global_store_dwordx4 v[20:21], v[2:5], off offset:2048
	s_waitcnt lgkmcnt(1)
	s_nop 0
	v_cvt_pk_bf16_f32 v2, v8, v9
	v_cvt_pk_bf16_f32 v3, v10, v11
	s_waitcnt lgkmcnt(0)
	v_cvt_pk_bf16_f32 v4, v12, v13
	v_or_b32_e32 v12, 8, v18
	v_ashrrev_i32_e32 v13, 31, v12
	v_lshlrev_b64 v[20:21], 12, v[12:13]
	v_cvt_pk_bf16_f32 v5, v14, v15
	ds_read_b128 v[8:11], v22 offset:6336
	ds_read_b128 v[12:15], v22 offset:6352
	v_lshl_add_u64 v[20:21], v[16:17], 0, v[20:21]
	global_store_dwordx4 v[20:21], v[2:5], off offset:2048
	s_waitcnt lgkmcnt(1)
	s_nop 0
	v_cvt_pk_bf16_f32 v2, v8, v9
	v_cvt_pk_bf16_f32 v3, v10, v11
	s_waitcnt lgkmcnt(0)
	v_cvt_pk_bf16_f32 v4, v12, v13
	v_or_b32_e32 v12, 12, v18
	v_ashrrev_i32_e32 v13, 31, v12
	v_lshlrev_b64 v[20:21], 12, v[12:13]
	v_cvt_pk_bf16_f32 v5, v14, v15
	ds_read_b128 v[8:11], v22 offset:8448
	ds_read_b128 v[12:15], v22 offset:8464
	v_lshl_add_u64 v[20:21], v[16:17], 0, v[20:21]
	global_store_dwordx4 v[20:21], v[2:5], off offset:2048
	s_waitcnt lgkmcnt(1)
	s_nop 0
	v_cvt_pk_bf16_f32 v2, v8, v9
	v_cvt_pk_bf16_f32 v3, v10, v11
	s_waitcnt lgkmcnt(0)
	v_cvt_pk_bf16_f32 v4, v12, v13
	v_or_b32_e32 v12, 16, v18
	v_ashrrev_i32_e32 v13, 31, v12
	v_lshlrev_b64 v[20:21], 12, v[12:13]
	v_cvt_pk_bf16_f32 v5, v14, v15
	ds_read_b128 v[8:11], v22 offset:10560
	ds_read_b128 v[12:15], v22 offset:10576
	v_lshl_add_u64 v[20:21], v[16:17], 0, v[20:21]
	global_store_dwordx4 v[20:21], v[2:5], off offset:2048
	s_waitcnt lgkmcnt(1)
	s_nop 0
	v_cvt_pk_bf16_f32 v2, v8, v9
	v_cvt_pk_bf16_f32 v3, v10, v11
	s_waitcnt lgkmcnt(0)
	v_cvt_pk_bf16_f32 v4, v12, v13
	v_or_b32_e32 v12, 20, v18
	v_ashrrev_i32_e32 v13, 31, v12
	v_lshlrev_b64 v[20:21], 12, v[12:13]
	v_cvt_pk_bf16_f32 v5, v14, v15
	ds_read_b128 v[8:11], v22 offset:12672
	ds_read_b128 v[12:15], v22 offset:12688
	v_lshl_add_u64 v[20:21], v[16:17], 0, v[20:21]
	global_store_dwordx4 v[20:21], v[2:5], off offset:2048
	s_waitcnt lgkmcnt(1)
	s_nop 0
	v_cvt_pk_bf16_f32 v2, v8, v9
	v_cvt_pk_bf16_f32 v3, v10, v11
	s_waitcnt lgkmcnt(0)
	v_cvt_pk_bf16_f32 v4, v12, v13
	v_or_b32_e32 v12, 24, v18
	v_ashrrev_i32_e32 v13, 31, v12
	v_lshlrev_b64 v[20:21], 12, v[12:13]
	v_cvt_pk_bf16_f32 v5, v14, v15
	ds_read_b128 v[8:11], v22 offset:14784
	ds_read_b128 v[12:15], v22 offset:14800
	v_lshl_add_u64 v[16:17], v[16:17], 0, v[20:21]
	global_store_dwordx4 v[16:17], v[2:5], off offset:2048
	s_waitcnt lgkmcnt(1)
	s_nop 0
	v_cvt_pk_bf16_f32 v2, v8, v9
	v_or_b32_e32 v8, 28, v18
	v_cvt_pk_bf16_f32 v3, v10, v11
	s_waitcnt lgkmcnt(0)
	v_cvt_pk_bf16_f32 v4, v12, v13
	v_cvt_pk_bf16_f32 v5, v14, v15
	v_mov_b64_e32 v[168:169], 0x100
	v_mov_b64_e32 v[170:171], 0xff
	v_mov_b32_e32 v194, 0x3c23d70a
	v_mov_b32_e32 v195, 0x2800
	v_mov_b64_e32 v[196:197], 0x580
